# static s_setprio 1 for waves 4-7 in the FoX (P13) and stick-breaking (P2) attention loops, reset to 0 at the end of each section
# baseline (speedup 1.0000x reference)
; #define LAS __attribute__((address_space(3)))
; __device__ __forceinline__ int lane_id() { int l; asm volatile("v_mbcnt_lo_u32_b32 %0, -1, 0\n\tv_mbcnt_hi_u32_b32 %0, -1, %0" : "=v"(l)); return l; }
; __device__ __forceinline__ int v_st(int k, int c) { const int kk = (k & ~0xC) | ((k & 4) << 1) | ((k & 8) >> 1); return ((kk >> 3) * 4 + (c >> 5)) * 512 + ((kk & 7) * 32 + (c & 31)) * 2; }
; __device__ __forceinline__ int v_rd_base(int lane) { return ((lane & 3) << 3) | (((lane >> 2) & 3) << 6) | (((lane >> 4) & 1) << 5) | (((lane >> 5) & 1) << 8); }
; __device__ __forceinline__ void sb_block(const bf16_t* Qb, const bf16_t* Kh, const bf16_t* Vh, bf16_t* Ob, int P0, char* lds, LAS unsigned char* ldsl, const int wid) {
;     const int lane = lane_id(), tid = wid * 64 + lane, r32 = lane & 31, hi = lane >> 5;
;     char* V_lds = lds; char* K_lds = lds + 2 * SHM_V;
;     volatile LAS int* flags = (volatile LAS int*)(ldsl + OFF_FLAG);
;     const int sr = tid >> 4, sc = (tid & 15) * 8, vst0 = v_st(sr, sc), vst1 = v_st(32 + sr, sc), kws = KSWZ(sr, sc * 2);
;     const int vb0 = (int)(uintptr_t)V_lds + v_rd_base(lane);
;     const int qlo = P0 + wid * QBLK, qrow = qlo + r32;
;     bf16x8 qr[8];
;     const unsigned loff = (unsigned)(sr * LDQ0 + sc) * 2u, qoff = (unsigned)((wid * QBLK + r32) * LDQ0 + hi * 8) * 2u;
; #pragma unroll
;     for (int d0 = 0; d0 < 8; ++d0) qr[d0] = GLD8(Qb, qoff + d0 * 32);
;     f32x16 o[4] = {};
;     float R = 1.f; bool wdone = false;
;     const int NT = P0 / KVBLK + 4;
; __global__ void __launch_bounds__(NTHR, 2) mega_fwd(Args) {
;     ...
;         {
;             WSBASE(); const bf16_t* QKV0 = WSP(bf16_t, WS_QKV0); bf16_t* CONCAT = WSP(bf16_t, WS_CONCAT);
;             for (int L = bx; L < NB * SB_H * (SEQ / 256); L += G) {
;                 const int qb = ((L >> 8) & 1) ? 15 - (L & 15) : (L & 15), bh = L >> 4, b = bh >> 4, h = bh & 15;
;                 const size_t tok0 = (size_t)b * SEQ;
;                 const bf16_t* Qb = QKV0 + (tok0 + qb * 256) * QKV0_LD + h * HD;
;                 const bf16_t* Kh = QKV0 + tok0 * QKV0_LD + 2048 + h * HD;
;                 const bf16_t* Vh = QKV0 + tok0 * QKV0_LD + 4096 + h * HD;
;                 bf16_t* Ob = CONCAT + (tok0 + qb * 256) * DM + W_SSM + h * HD;
;                 att::sb_block(Qb, Kh, Vh, Ob, qb * 256, (char*)lds_raw, lds, wave);
.LBB0_289:
	s_mov_b64 s[6:7], s[0:1]
	s_andn2_b64 vcc, exec, s[14:15]
	s_cbranch_vccnz .LBB0_429
	v_readlane_b32 s32, v248, 4
	s_nop 3
	s_cmp_ge_u32 s32, 4
	s_cbranch_scc0 .Lprio2_done
	s_setprio 1
.Lprio2_done:
	s_load_dwordx2 s[16:17], s[6:7], 0xb0
	v_mbcnt_lo_u32_b32 v0, -1, 0
	s_movk_i32 s19, 0x3000
	s_movk_i32 s24, 0xc0
	s_movk_i32 s25, 0x1800
	s_waitcnt lgkmcnt(0)
	s_add_u32 s26, s16, 1.0
	s_addc_u32 s27, s17, 0
	s_lshl_b32 s6, s92, 2
	s_add_i32 s30, s6, 0
	s_add_i32 s30, s30, 0x10800
	s_movk_i32 s31, 0x80
	v_mov_b32_e32 v145, 0
	s_movk_i32 s44, 0x70
	s_mov_b32 s18, 0x3e0293ee
	s_mov_b32 s45, 0x2b800000
	s_add_i32 s46, 0, 0x10804
	s_add_i32 s47, 0, 0x10808
	s_add_i32 s52, 0, 0x1080c
	s_add_i32 s53, 0, 0x10810
	s_add_i32 s54, 0, 0x10814
	s_add_i32 s55, 0, 0x10818
	s_add_i32 s56, 0, 0x1081c
	v_mbcnt_hi_u32_b32 v156, -1, v0
	s_mov_b64 s[20:21], 0x53801000
	s_mov_b32 s57, 0x8000
	v_mov_b32_e32 v157, 0xff800000
	v_mov_b32_e32 v158, 0xf0
	s_mov_b32 s58, s2
	s_branch .LBB0_292

; #define GRID_BAR() do { WSBASE(); XcdBarrier bar_; bar_.bar = (unsigned*)(wsb + WS_CTL) + CW_BAR; bar_.x = xb_xcc_id(); bar_.st = MISC + 8; xcd_barrier(bar_, wave == 0 && lane_id() == 0); } while (0)
; #define GRID_BAR() do {} while (0)
; #define BOTH(k) (IN(k) && IN((k) + 1))
; __device__ __forceinline__ void xcd_barrier(const XcdBarrier& b, const bool t0) {
;     asm volatile("s_waitcnt vmcnt(0)" ::: "memory");
;     __syncthreads();
;     if (t0) {
;         unsigned* bar = b.bar;
;         __builtin_amdgcn_s_waitcnt(0);
;         unsigned nloc = b.st[0], nx = b.st[1];
;         if (nloc == 0u) { xcd_barrier_complete(bar, b.x, nloc, nx); b.st[0] = nloc; b.st[1] = nx; }
; __global__ void __launch_bounds__(NTHR, 2) mega_fwd(Args) {
;     ...
;         if (BOTH(2)) GRID_BAR();
.LBB0_429:
	s_setprio 0
	s_cmp_gt_i32 s85, 3
	s_cbranch_scc0 .LBB0_485
	s_mov_b64 s[6:7], s[0:1]
	s_load_dwordx2 s[8:9], s[6:7], 0xb0
	s_mov_b64 s[10:11], 0
	s_andn2_b64 vcc, exec, s[86:87]
	s_getreg_b32 s12, hwreg(HW_REG_XCC_ID, 0, 4)
	s_cbranch_vccnz .LBB0_432
	v_mbcnt_lo_u32_b32 v0, -1, 0
	v_mbcnt_hi_u32_b32 v0, -1, v0
	s_nop 0
	v_cmp_eq_u32_e32 vcc, 0, v0
	s_and_b64 s[10:11], vcc, exec

; #define LAS __attribute__((address_space(3)))
; __device__ __forceinline__ int lane_id() { int l; asm volatile("v_mbcnt_lo_u32_b32 %0, -1, 0\n\tv_mbcnt_hi_u32_b32 %0, -1, %0" : "=v"(l)); return l; }
; #define WSBASE() const AS4 unsigned char* kp_ = (const AS4 unsigned char*)__builtin_amdgcn_kernarg_segment_ptr(); asm volatile("" : "+s"(kp_)); \
;                  unsigned char* wsb = *(unsigned char* const AS4*)(kp_ + 176); float* outp = *(float* const AS4*)(kp_ + 168); (void)outp; (void)wsb
; __device__ __forceinline__ bool fox_item(int bx, int k, int G, int total, int& bh, int& y) {
;     if (G == 256) { if (k >= 4) return false; const int x = bx & 7, c = bx >> 3, i = c & 7, sft = 4 * ((k + (i >> 1)) & 3);
;         bh = 16 * x + (c >> 3) + 4 * k; y = ((i & 1) ? (0x6521 >> sft) : (0x7430 >> sft)) & 0xf; return true; }
;     const int L = bx + k * G; if (L >= total) return false; bh = L >> 3; y = L & 7; return true;
; __global__ void __launch_bounds__(NTHR, 2) mega_fwd(Args) {
;     ...
;     for (int rep_ = 0; rep_ < NREP(13); ++rep_) if (IN(13)) {
;         WSBASE(); const bf16_t* QKV1 = WSP(bf16_t, WS_QKV1); bf16_t* ATT = WSP(bf16_t, WS_ATT); const float* CB = WSP(float, WS_CB);
;         const int total = NB * FOX_H * 8;
;         if (bx < total) {
;             volatile LAS int* JLO = (volatile LAS int*)(lds + MISC_OFF) + 16;
;             {
;                 const int lane = lane_id(); int bh, y;
;                 if (att::fox_item(bx, wave >> 1, G, total, bh, y)) {
;                     const int qb = (wave & 1) ? 15 - y : y, P0 = qb * 256;
.LBB0_1117:
	s_cmp_lt_i32 s84, 14
	s_cselect_b64 s[4:5], -1, 0
	s_and_b64 s[4:5], s[4:5], s[56:57]
	s_cmp_gt_i32 s85, 14
	s_waitcnt lgkmcnt(0)
	s_cselect_b64 s[14:15], -1, 0
	s_andn2_b64 vcc, exec, s[4:5]
	s_cbranch_vccnz .LBB0_1421
	v_readlane_b32 s32, v248, 4
	s_nop 3
	s_cmp_ge_u32 s32, 4
	s_cbranch_scc0 .Lprio13_done
	s_setprio 1
.Lprio13_done:
	s_mov_b64 s[8:9], s[0:1]
	s_and_b64 vcc, exec, s[38:39]
	s_cbranch_vccnz .LBB0_1365
	s_load_dwordx2 s[20:21], s[8:9], 0xb0
	v_mbcnt_lo_u32_b32 v0, -1, 0
	v_mbcnt_hi_u32_b32 v0, -1, v0
	s_waitcnt lgkmcnt(0)
	s_add_u32 s49, s20, 0x31600000
	s_addc_u32 s53, s21, 0
	s_lshr_b32 s4, s42, 7
	s_cmpk_eq_i32 s40, 0x100
	s_cselect_b64 s[18:19], -1, 0
	s_cmpk_lg_i32 s40, 0x100
	s_cselect_b64 s[16:17], -1, 0
	s_lshl_b32 s5, s2, 4
	s_ashr_i32 s6, s2, 6
	s_and_b32 s76, s5, 0x70
	s_bitcmp0_b32 s2, 3
	s_movk_i32 s5, 0x7430
	s_cselect_b32 s74, s5, 0x6521
	s_and_b64 vcc, exec, s[16:17]
	s_cbranch_vccz .LBB0_1121
	s_mul_i32 s5, s40, s4
	s_add_i32 s5, s5, s2
	s_cmpk_lt_i32 s5, 0x400
	s_cselect_b64 s[12:13], -1, 0
	s_cmpk_gt_i32 s5, 0x3ff
	s_cselect_b64 s[10:11], -1, 0
	s_ashr_i32 s8, s5, 3
	s_mov_b64 s[22:23], 0
	s_branch .LBB0_1122

; #define WSBASE() const AS4 unsigned char* kp_ = (const AS4 unsigned char*)__builtin_amdgcn_kernarg_segment_ptr(); asm volatile("" : "+s"(kp_)); \
;                  unsigned char* wsb = *(unsigned char* const AS4*)(kp_ + 176); float* outp = *(float* const AS4*)(kp_ + 168); (void)outp; (void)wsb
; #define GRID_BAR() do { WSBASE(); XcdBarrier bar_; bar_.bar = (unsigned*)(wsb + WS_CTL) + CW_BAR; bar_.x = xb_xcc_id(); bar_.st = MISC + 8; xcd_barrier(bar_, wave == 0 && lane_id() == 0); } while (0)
; #define GRID_BAR() do {} while (0)
; #define BOTH(k) (IN(k) && IN((k) + 1))
; __global__ void __launch_bounds__(NTHR, 2) mega_fwd(Args) {
;     ...
;         if (BOTH(13)) GRID_BAR();
;     }
;     for (int rep_ = 0; rep_ < NREP(14); ++rep_) if (IN(14)) {
;         WSBASE();
;         pg8::Gemm g{WSP(bf16_t, WS_ATT), WSP(bf16_t, WS_W_OUT1), DM, 64, DM, pg8::BK * 2, 0, 32768, (size_t)BM_ * DM * 2}; pg8::StaticOrder S; S.init(MTOK, DM, G, bx);
.LBB0_1421:
	s_setprio 0
	s_waitcnt lgkmcnt(0)
	s_cmp_lt_i32 s84, 15
	s_cselect_b64 s[4:5], -1, 0
	s_and_b64 s[4:5], s[4:5], s[14:15]
	s_andn2_b64 vcc, exec, s[4:5]
	s_cbranch_vccnz .LBB0_1554
	s_mov_b64 s[8:9], s[0:1]
	s_and_b64 vcc, exec, s[38:39]
	v_mbcnt_lo_u32_b32 v0, -1, 0
	v_mbcnt_hi_u32_b32 v0, -1, v0
	s_cbranch_vccz .LBB0_1425
	s_and_b64 vcc, exec, s[38:39]
	s_cbranch_vccz .LBB0_1426
